# modulate phase (layer-0 group loop copy): the 8-step shift/scale ladder (store, 2 loads, wait per step) de-serialised - all 14 later shift/scale loads issued with the row loads into dead VGPRs, one wa
# baseline (speedup 1.0000x reference)
;   DI const float* x() const { return (const float*)sp[0]; }
;   DI const float* ctx() const { return (const float*)sp[2]; }
;   DI const float* ln_g() const { return (const float*)sp[6]; }
;   DI const float* ln_b() const { return (const float*)sp[7]; }
; DI unsigned cvtpk(float lo, float hi) { f32x2_t v = {lo, hi}; bf16x2_t b = __builtin_convertvector(v, bf16x2_t); return __builtin_bit_cast(unsigned, b); }
; DI void phase_mod(const Params& p, int g, int layer, char* smem) {
;     ...
;       const float* s = t < CTX ? p.ctx() + ((long)b * CTX + t) * DM : p.x() + ((long)b * SEQ + (t - CTX)) * DM;
; #pragma unroll
;       for (int j = 0; j < 8; ++j) { const f32x4 a = *(const f32x4*)(s + lane * 4 + 256 * j); v[4 * j] = a[0]; v[4 * j + 1] = a[1]; v[4 * j + 2] = a[2]; v[4 * j + 3] = a[3]; }
;     } else {
;       float* s = P_ZX + r * DM;
; #pragma unroll
;       for (int j = 0; j < 8; ++j) { const f32x4 a = *(const f32x4*)(s + lane * 4 + 256 * j); v[4 * j] = a[0]; v[4 * j + 1] = a[1]; v[4 * j + 2] = a[2]; v[4 * j + 3] = a[3]; }
;       row_ln(v, p.ln_g(), p.ln_b(), lane);
; #pragma unroll
;       for (int j = 0; j < 8; ++j) { const f32x4 o = {v[4 * j], v[4 * j + 1], v[4 * j + 2], v[4 * j + 3]}; *(f32x4*)(s + lane * 4 + 256 * j) = o; }
;     }
;     const float* md = P_MOD + ((long)layer * 9 + (t < CTX ? 8 : b)) * 6144;
; #pragma unroll
;     for (int j = 0; j < 8; ++j) {
;       const f32x4 sh = *(const f32x4*)(md + lane * 4 + 256 * j), sc = *(const f32x4*)(md + 2048 + lane * 4 + 256 * j);
;       u32x2 o = {cvtpk(v[4 * j] * (1.f + sc[0]) + sh[0], v[4 * j + 1] * (1.f + sc[1]) + sh[1]), cvtpk(v[4 * j + 2] * (1.f + sc[2]) + sh[2], v[4 * j + 3] * (1.f + sc[3]) + sh[3])};
;       *reinterpret_cast<u32x2*>(h + (long)i * DM + lane * 4 + 256 * j) = o;
.LBB0_825:
	s_or_b64 exec, exec, s[2:3]
	ds_read_b64 v[2:3], v6
	v_lshlrev_b64 v[0:1], 13, v[0:1]
	v_mov_b32_e32 v29, v129
	v_readlane_b32 s2, v254, 23
	v_readlane_b32 s3, v254, 24
	s_waitcnt lgkmcnt(0)
	v_lshl_add_u64 v[0:1], v[2:3], 0, v[0:1]
	v_lshl_add_u64 v[0:1], v[0:1], 0, v[28:29]
	global_load_dwordx4 v[34:37], v[0:1], off
	global_load_dwordx4 v[38:41], v[0:1], off offset:1024
	global_load_dwordx4 v[20:23], v[0:1], off offset:2048
	global_load_dwordx4 v[16:19], v[0:1], off offset:3072
	v_add_co_u32_e32 v0, vcc, 0x1000, v0
	v_lshl_add_u64 v[30:31], s[2:3], 0, v[30:31]
	s_nop 0
	v_addc_co_u32_e32 v1, vcc, 0, v1, vcc
	v_lshl_add_u64 v[50:51], v[30:31], 0, v[28:29]
	s_movk_i32 s2, 0x3000
	v_add_co_u32_e32 v32, vcc, s2, v50
	global_load_dwordx4 v[12:15], v[0:1], off
	global_load_dwordx4 v[8:11], v[0:1], off offset:1024
	global_load_dwordx4 v[4:7], v[0:1], off offset:2048
	s_nop 0
	global_load_dwordx4 v[0:3], v[0:1], off offset:3072
	v_addc_co_u32_e32 v33, vcc, 0, v51, vcc
	global_load_dwordx4 v[42:45], v[50:51], off
	global_load_dwordx4 v[46:49], v[32:33], off offset:-4096
	v_lshlrev_b64 v[30:31], 12, v[24:25]
	v_lshl_add_u64 v[30:31], v[26:27], 0, v[30:31]
	v_lshl_add_u64 v[52:53], v[50:51], 0, s[90:91]
	s_movk_i32 s2, 0x1000
	v_add_u32_e32 v24, s80, v24
	global_load_dwordx4 v[56:59], v[50:51], off offset:1024
	global_load_dwordx4 v[60:63], v[52:53], off offset:1024
	global_load_dwordx4 v[64:67], v[50:51], off offset:2048
	global_load_dwordx4 v[68:71], v[52:53], off offset:2048
	global_load_dwordx4 v[80:83], v[50:51], off offset:3072
	global_load_dwordx4 v[84:87], v[52:53], off offset:3072
	global_load_dwordx4 v[88:91], v[52:53], off offset:-4096
	global_load_dwordx4 v[120:123], v[32:33], off
	global_load_dwordx4 v[124:127], v[52:53], off offset:-3072
	global_load_dwordx4 v[184:187], v[32:33], off offset:1024
	global_load_dwordx4 v[228:231], v[52:53], off offset:-2048
	global_load_dwordx4 v[232:235], v[32:33], off offset:2048
	global_load_dwordx4 v[236:239], v[52:53], off offset:-1024
	global_load_dwordx4 v[240:243], v[32:33], off offset:3072
	s_waitcnt vmcnt(0)
	v_pk_add_f32 v[46:47], v[46:47], 1.0 op_sel_hi:[1,0]
	s_waitcnt lgkmcnt(0)
	v_pk_fma_f32 v[34:35], v[34:35], v[46:47], v[42:43]
	v_pk_add_f32 v[42:43], v[48:49], 1.0 op_sel_hi:[1,0]
	v_cvt_pk_bf16_f32 v34, v34, v35
	v_pk_fma_f32 v[36:37], v[36:37], v[42:43], v[44:45]
	s_nop 0
	v_cvt_pk_bf16_f32 v35, v36, v37
	global_store_dwordx2 v[30:31], v[34:35], off
	s_nop 0
	v_pk_add_f32 v[60:61], v[60:61], 1.0 op_sel_hi:[1,0]
	s_nop 0
	v_pk_fma_f32 v[56:57], v[38:39], v[60:61], v[56:57]
	v_pk_add_f32 v[38:39], v[62:63], 1.0 op_sel_hi:[1,0]
	v_cvt_pk_bf16_f32 v56, v56, v57
	v_pk_fma_f32 v[58:59], v[40:41], v[38:39], v[58:59]
	s_nop 0
	v_cvt_pk_bf16_f32 v57, v58, v59
	global_store_dwordx2 v[30:31], v[56:57], off offset:512
	s_nop 0
	v_pk_add_f32 v[68:69], v[68:69], 1.0 op_sel_hi:[1,0]
	s_nop 0
	v_pk_fma_f32 v[20:21], v[20:21], v[68:69], v[64:65]
	v_pk_add_f32 v[64:65], v[70:71], 1.0 op_sel_hi:[1,0]
	v_cvt_pk_bf16_f32 v20, v20, v21
	v_pk_fma_f32 v[22:23], v[22:23], v[64:65], v[66:67]
	s_nop 0
	v_cvt_pk_bf16_f32 v21, v22, v23
	global_store_dwordx2 v[30:31], v[20:21], off offset:1024
	s_nop 0
	v_pk_add_f32 v[84:85], v[84:85], 1.0 op_sel_hi:[1,0]
	s_nop 0
	v_pk_fma_f32 v[16:17], v[16:17], v[84:85], v[80:81]
	v_pk_add_f32 v[80:81], v[86:87], 1.0 op_sel_hi:[1,0]
	v_cvt_pk_bf16_f32 v16, v16, v17
	v_pk_fma_f32 v[18:19], v[18:19], v[80:81], v[82:83]
	v_add_co_u32_e32 v84, vcc, s2, v50
	v_cvt_pk_bf16_f32 v17, v18, v19
	global_store_dwordx2 v[30:31], v[16:17], off offset:1536
	v_addc_co_u32_e32 v85, vcc, 0, v51, vcc
	s_movk_i32 s2, 0x11ff
	v_cmp_lt_i32_e32 vcc, s2, v24
	s_or_b64 s[6:7], vcc, s[6:7]
	v_pk_add_f32 v[120:121], v[120:121], 1.0 op_sel_hi:[1,0]
	s_nop 0
	v_pk_fma_f32 v[12:13], v[12:13], v[120:121], v[88:89]
	v_pk_add_f32 v[88:89], v[122:123], 1.0 op_sel_hi:[1,0]
	v_cvt_pk_bf16_f32 v12, v12, v13
	v_pk_fma_f32 v[14:15], v[14:15], v[88:89], v[90:91]
	s_nop 0
	v_cvt_pk_bf16_f32 v13, v14, v15
	global_store_dwordx2 v[30:31], v[12:13], off offset:2048
	s_nop 0
	v_pk_add_f32 v[184:185], v[184:185], 1.0 op_sel_hi:[1,0]
	s_nop 0
	v_pk_fma_f32 v[8:9], v[8:9], v[184:185], v[124:125]
	v_pk_add_f32 v[124:125], v[186:187], 1.0 op_sel_hi:[1,0]
	v_cvt_pk_bf16_f32 v8, v8, v9
	v_pk_fma_f32 v[10:11], v[10:11], v[124:125], v[126:127]
	s_nop 0
	v_cvt_pk_bf16_f32 v9, v10, v11
	global_store_dwordx2 v[30:31], v[8:9], off offset:2560
	s_nop 0
	v_pk_add_f32 v[232:233], v[232:233], 1.0 op_sel_hi:[1,0]
	s_nop 0
	v_pk_fma_f32 v[4:5], v[4:5], v[232:233], v[228:229]
	v_pk_add_f32 v[228:229], v[234:235], 1.0 op_sel_hi:[1,0]
	v_cvt_pk_bf16_f32 v4, v4, v5
	v_pk_fma_f32 v[6:7], v[6:7], v[228:229], v[230:231]
	s_nop 0
	v_cvt_pk_bf16_f32 v5, v6, v7
	global_store_dwordx2 v[30:31], v[4:5], off offset:3072
	s_nop 0
	v_pk_add_f32 v[240:241], v[240:241], 1.0 op_sel_hi:[1,0]
	s_nop 0
	v_pk_fma_f32 v[0:1], v[0:1], v[240:241], v[236:237]
	v_pk_add_f32 v[236:237], v[242:243], 1.0 op_sel_hi:[1,0]
	v_cvt_pk_bf16_f32 v0, v0, v1
	v_pk_fma_f32 v[2:3], v[2:3], v[236:237], v[238:239]
	s_nop 0
	v_cvt_pk_bf16_f32 v1, v2, v3
	global_store_dwordx2 v[30:31], v[0:1], off offset:3584
	s_andn2_b64 exec, exec, s[6:7]
	s_cbranch_execz .LBB0_830
